# ffn2 weight copies moved out of the FFN-down / w_in GEMM tails to the attention phase start (all 256 workgroups), code shared via s98 return selector
# baseline (speedup 1.0000x reference)
_Z8mega_fwd6Params:
	s_mov_b32 s98, 0
	s_load_dwordx2 s[42:43], s[0:1], 0x118
	s_load_dword s72, s[0:1], 0x120
	s_add_u32 s4, s0, 0x118
	s_addc_u32 s5, s1, 0
	v_and_b32_e32 v218, 0x3ff, v0
	v_writelane_b32 v252, s4, 0
	v_readfirstlane_b32 s75, v218
	v_cmp_gt_u32_e32 vcc, 2, v218
	v_writelane_b32 v252, s5, 1
	s_and_saveexec_b64 s[4:5], vcc
	v_lshlrev_b32_e32 v1, 2, v218
	v_mov_b32_e32 v2, 0
	ds_write_b32 v1, v2
	s_or_b64 exec, exec, s[4:5]
	s_mov_b64 s[4:5], s[0:1]
	s_waitcnt lgkmcnt(0)
	s_barrier
	s_load_dwordx2 s[40:41], s[4:5], 0x110
	s_getreg_b32 s3, hwreg(HW_REG_XCC_ID, 0, 4)
	s_and_b32 s33, s3, 15
	v_cmp_eq_u32_e64 s[4:5], 0, v218
	s_and_saveexec_b64 s[6:7], s[4:5]
	s_cbranch_execz .LBB0_5
	s_mov_b64 s[8:9], exec
	v_mbcnt_lo_u32_b32 v1, s8, 0
	v_mbcnt_hi_u32_b32 v1, s9, v1
	v_cmp_eq_u32_e32 vcc, 0, v1
	s_and_b64 s[10:11], exec, vcc
	s_mov_b64 exec, s[10:11]
	s_cbranch_execz .LBB0_5
	s_lshl_b32 s3, s33, 8
	s_bcnt1_i32_b64 s8, s[8:9]
	v_mov_b32_e32 v1, s3
	v_mov_b32_e32 v2, s8
	s_waitcnt lgkmcnt(0)
	global_atomic_add v1, v2, s[40:41] offset:1024

.Lfilt_copies:
	s_cmpk_lg_i32 s42, 0x100
	s_cbranch_scc1 .Lfilt_copies_generic
	s_branch .LBB0_408

.LBB0_408:
	s_cmp_eq_u32 s98, 1
	s_cbranch_scc1 .Lmv_ret1
	s_waitcnt vmcnt(0)
	s_barrier
	s_and_saveexec_b64 s[6:7], s[4:5]
	s_cbranch_execz .LBB0_460
	v_mov_b32_e32 v18, 0
	s_waitcnt vmcnt(0) expcnt(0) lgkmcnt(0)
	ds_read_b32 v4, v18
	ds_read_b32 v2, v18 offset:4
	s_waitcnt lgkmcnt(1)
	v_cmp_ne_u32_e32 vcc, 0, v4
	s_cbranch_vccnz .LBB0_424
	s_add_u32 s8, s40, 0x1000
	s_addc_u32 s9, s41, 0
	s_add_u32 s10, s40, 0x1100
	s_addc_u32 s11, s41, 0
	s_add_u32 s12, s40, 0x1200
	s_addc_u32 s13, s41, 0
	s_mul_i32 s22, s43, s72
	s_add_u32 s14, s40, 0x1300
	s_mul_i32 s22, s22, s42
	s_addc_u32 s15, s41, 0
	s_mov_b32 s23, 1
	s_branch .LBB0_412

.LBB0_671:
	s_mul_hi_u32 s6, s77, 0x780
	s_mul_i32 s6, s6, s76
	s_sub_i32 s6, 0x780, s6
	s_sub_i32 s7, s6, s76
	s_cmp_ge_u32 s6, s76
	s_cselect_b32 s6, s7, s6
	s_sub_i32 s7, s6, s76
	s_cmp_ge_u32 s6, s76
	s_cselect_b32 s10, s7, s6
	s_sub_i32 s11, s42, s10
	s_cmp_lt_i32 s2, s10
	s_cselect_b64 s[6:7], -1, 0
	s_and_b64 s[8:9], s[6:7], exec
	s_cselect_b32 s11, 0, s11
	s_cmp_eq_u32 s10, 0
	s_cselect_b64 s[8:9], -1, 0
	s_waitcnt lgkmcnt(0)
	s_and_b64 s[18:19], s[8:9], exec
	s_cselect_b32 s18, s42, s11
	s_cmpk_lg_i32 s42, 0x100
	s_cbranch_scc0 .LBB0_687
	s_cmp_eq_u32 s18, 0
	s_cbranch_scc1 .LBB0_687
	s_sub_i32 s10, s2, s10
	s_and_b64 s[6:7], s[6:7], exec
	s_cselect_b32 s10, 0, s10
	s_and_b64 s[6:7], s[8:9], exec
	s_cselect_b32 s6, s2, s10
.Lwin_entry:
	s_lshl_b32 s7, s6, 3
	s_add_i32 s22, s7, s3
	s_cmpk_gt_i32 s22, 0x157f
	s_cbranch_scc1 .LBB0_687
	s_lshl_b32 s23, s18, 3
	s_add_u32 s8, s26, 0x5000000
	s_addc_u32 s9, s27, 0
	s_add_u32 s10, s26, 0x7b00000
	s_addc_u32 s11, s27, 0
	s_lshl_b32 s7, s22, 3
	s_add_i32 s27, s7, 0x16000
	s_lshl_b32 s6, s6, 6
	s_lshl_b32 s7, s3, 3
	s_add_i32 s26, s22, 0x1600
	s_lshl_b32 s28, s18, 6
	s_add_i32 s29, s6, s7
	s_movk_i32 s30, 0x1580
	v_mov_b32_e32 v3, 0
	s_movk_i32 s31, 0x2000
	s_mov_b32 s19, 0
	s_movk_i32 s34, 0x4000
	s_movk_i32 s35, 0x6000
	s_mov_b32 s36, 0x8000
	s_mov_b32 s37, 0xa000
	s_mov_b32 s38, 0xc000
	s_mov_b32 s39, 0xe000
	s_movk_i32 s44, 0x2b00
	s_movk_i32 s47, 0x7fff
	s_mov_b32 s50, 0xffff0000
	s_movk_i32 s51, 0x5000
	s_movk_i32 s54, 0x3f00
	s_mov_b32 s55, 0x10000
	s_mov_b32 s56, 0x15000
	s_mov_b32 s57, 0x1a000
	s_mov_b32 s58, 0x20000
	s_mov_b32 s59, 0x25000
	s_movk_i32 s60, 0xff00
	v_mov_b32_e32 v6, 0x80000
	s_branch .LBB0_676

.LBB0_687:
	s_cmp_eq_u32 s98, 2
	s_cbranch_scc1 .Lmv_ret2
	s_waitcnt vmcnt(0)
	s_waitcnt vmcnt(0)
	s_barrier
	s_and_saveexec_b64 s[6:7], s[4:5]
	s_cbranch_execz .LBB0_739
	v_mov_b32_e32 v18, 0
	s_waitcnt vmcnt(0) expcnt(0) lgkmcnt(0)
	ds_read_b32 v4, v18
	ds_read_b32 v2, v18 offset:4
	s_waitcnt lgkmcnt(1)
	v_cmp_ne_u32_e32 vcc, 0, v4
	s_cbranch_vccnz .LBB0_703
	s_add_u32 s8, s40, 0x1000
	s_addc_u32 s9, s41, 0
	s_add_u32 s10, s40, 0x1100
	s_addc_u32 s11, s41, 0
	s_add_u32 s12, s40, 0x1200
	s_addc_u32 s13, s41, 0
	s_mul_i32 s22, s43, s72
	s_add_u32 s14, s40, 0x1300
	s_mul_i32 s22, s22, s42
	s_addc_u32 s15, s41, 0
	s_mov_b32 s23, 1
	s_branch .LBB0_691

.LBB0_739:
	s_or_b64 exec, exec, s[6:7]
	s_mov_b64 s[6:7], s[0:1]
	s_waitcnt lgkmcnt(0)
	s_barrier
	s_cmpk_lg_i32 s42, 0x100
	s_cbranch_scc1 .Lmv_skip
	s_load_dwordx4 s[20:23], s[0:1], 0xf0
	s_load_dwordx2 s[26:27], s[0:1], 0x110
	s_mov_b32 s98, 1
	s_mov_b32 s47, s2
	s_movk_i32 s44, 0x100
	s_waitcnt lgkmcnt(0)
	s_branch .LBB0_395
.Lmv_ret1:
	s_load_dwordx8 s[12:19], s[0:1], 0xf0
	s_load_dwordx2 s[26:27], s[0:1], 0x110
	s_mov_b32 s98, 2
	s_mov_b32 s6, s2
	s_waitcnt lgkmcnt(0)
	s_movk_i32 s18, 0x100
	s_branch .Lwin_entry
.Lmv_ret2:
	s_mov_b32 s98, 0
	s_mov_b64 s[6:7], s[0:1]
.Lmv_skip:
	s_load_dwordx4 s[20:23], s[6:7], 0x80
	s_load_dwordx2 s[18:19], s[6:7], 0x90
	s_load_dwordx2 s[26:27], s[6:7], 0x110
	s_add_i32 s6, s42, 0x3ff
	s_ashr_i32 s7, s6, 31
	s_abs_i32 s6, s6
	s_mul_hi_u32 s8, s6, s77
	s_mul_i32 s9, s8, s76
	s_sub_i32 s6, s6, s9
	s_xor_b32 s7, s7, s45
	s_add_i32 s9, s8, 1
	s_sub_i32 s10, s6, s76
	s_cmp_ge_u32 s6, s76
	s_cselect_b32 s8, s9, s8
	s_cselect_b32 s6, s10, s6
	s_add_i32 s9, s8, 1
	s_cmp_ge_u32 s6, s76
	v_add_u32_e32 v2, 0x200, v218
	s_cselect_b32 s6, s9, s8
	s_movk_i32 s8, 0x90
	v_lshrrev_b32_e32 v3, 3, v2
	v_lshlrev_b32_e32 v184, 6, v3
	v_mad_u32_u24 v181, v3, s8, 16
	v_or_b32_e32 v3, 0x400, v218
	s_xor_b32 s6, s6, s7
	v_lshrrev_b32_e32 v4, 3, v3
	s_sub_i32 s44, s6, s7
	v_lshlrev_b32_e32 v185, 6, v4
	v_mad_u32_u24 v182, v4, s8, 16
	v_add_u32_e32 v4, 0x600, v218
	s_waitcnt lgkmcnt(0)
	s_add_u32 s28, s26, 0xe100000
	v_lshrrev_b32_e32 v226, 3, v218
	v_lshrrev_b32_e32 v5, 3, v4
	s_addc_u32 s29, s27, 0
	v_mad_u32_u24 v180, v226, s8, 16
	v_mad_u32_u24 v190, v5, s8, 16
	s_movk_i32 s8, 0x280
	v_lshrrev_b32_e32 v2, 5, v2
	s_add_u32 s30, s26, 0x24900000
	v_lshlrev_b32_e32 v193, 8, v2
	v_mad_u32_u24 v189, v2, s8, 16
	v_lshrrev_b32_e32 v2, 5, v3
	s_addc_u32 s31, s27, 0
	v_and_b32_e32 v201, 7, v218
	s_movk_i32 s6, 0x600
	v_and_b32_e32 v225, 31, v218
	v_lshrrev_b32_e32 v228, 5, v218
	v_lshlrev_b32_e32 v192, 8, v2
	v_mad_u32_u24 v186, v2, s8, 16
	v_lshrrev_b32_e32 v2, 5, v4
	v_and_b32_e32 v197, 15, v218
	v_lshrrev_b32_e32 v196, 4, v198
	s_cmp_lt_i32 s44, 1
	v_lshlrev_b32_e32 v183, 6, v226
	v_mov_b32_e32 v139, 0
	v_lshlrev_b32_e32 v227, 3, v201
	v_lshlrev_b32_e32 v177, 4, v201
	v_cmp_gt_u32_e64 s[6:7], s6, v3
	v_lshlrev_b32_e32 v176, 6, v5
	v_lshlrev_b32_e32 v194, 8, v228
	v_lshlrev_b32_e32 v229, 3, v225
	v_mad_u32_u24 v188, v228, s8, 16
	v_lshlrev_b32_e32 v179, 4, v225
	v_lshlrev_b32_e32 v178, 8, v2
	v_mad_u32_u24 v191, v2, s8, 16
	v_lshlrev_b32_e32 v187, 2, v196
	v_lshlrev_b32_e32 v195, 3, v196
	v_and_b32_e32 v202, 48, v218
	v_lshlrev_b32_e32 v140, 3, v197
	s_cbranch_scc1 .LBB0_812
	s_lshr_b32 s10, s75, 7
	s_and_b32 s50, s10, 0x1fffffe
	s_bfe_u32 s51, s75, 0x20006
	s_cmp_eq_u32 s51, 2
	s_cselect_b32 s66, 24, 32
	s_lshl_b32 s10, s51, 4
	s_add_i32 s11, 16, 0x13000
	v_or_b32_e32 v2, s10, v197
	s_add_u32 s67, s26, 0x900000
	v_med3_u32 v3, v2, 8, 56
	s_addc_u32 s68, s27, 0
	v_add_u32_e32 v203, -8, v3
	v_add_u32_e32 v204, 8, v3
	s_add_u32 s69, s26, 0xb00000
	v_mul_u32_u24_e32 v3, 0x90, v197
	s_addc_u32 s70, s27, 0
	v_add3_u32 v207, v3, v202, 16
	v_mul_u32_u24_e32 v3, 0x280, v196
	s_add_u32 s71, s26, 0x11100000
	v_or_b32_e32 v3, v3, v140
	s_addc_u32 s76, s27, 0
	v_add_u32_e32 v3, 16, v3
	s_add_u32 s77, s26, 0x13900000
	v_add_u32_e32 v208, 0x9000, v3
	v_sub_u32_e32 v3, v187, v197
	s_addc_u32 s78, s27, 0
	v_subrev_u32_e32 v209, s10, v3
	s_lshr_b32 s10, s75, 8
	s_mulk_i32 s10, 0xff08
	v_lshl_or_b32 v138, v197, 7, v202
	v_lshl_add_u32 v206, v218, 2, s11
	s_add_i32 s75, s10, 16
	v_lshl_add_u64 v[6:7], s[26:27], 0, v[138:139]
	s_mov_b64 s[10:11], 0x110fc800
	v_mov_b32_e32 v141, v139
	s_mul_i32 s47, s44, s2
	s_movk_i32 s8, 0x1d1
	v_or_b32_e32 v205, 0x1000, v2
	v_lshlrev_b32_e32 v2, 6, v197
	v_lshlrev_b32_e32 v4, 2, v197
	v_lshl_add_u64 v[142:143], v[6:7], 0, s[10:11]
	v_lshl_add_u64 v[6:7], s[26:27], 0, v[140:141]
	s_mov_b64 s[10:11], 0x138fc800
	v_cmp_gt_u32_e64 s[8:9], s8, v218
	s_lshl_b32 s79, s47, 2
	v_add_u32_e32 v210, 19, v209
	v_add_u32_e32 v211, 3, v209
	v_add_u32_e32 v212, 18, v209
	v_add_u32_e32 v213, 2, v209
	v_add_u32_e32 v214, 17, v209
	v_add_u32_e32 v215, 1, v209
	v_add_u32_e32 v216, 16, v209
	v_lshl_add_u64 v[144:145], v[6:7], 0, s[10:11]
	s_mov_b32 s37, 0
	s_mov_b32 s84, -1
	s_mov_b32 s80, 0x20000
	v_lshlrev_b32_e32 v146, 1, v2
	v_lshlrev_b32_e32 v148, 1, v4
	s_mov_b64 s[38:39], 0x2000
	s_movk_i32 s81, 0x7fff
	s_mov_b32 s82, 0xffff0000
	s_mov_b64 s[54:55], 0x20000
	v_mbcnt_hi_u32_b32 v141, -1, v224
	s_mov_b32 s83, 0
	s_branch .LBB0_743
